# stack28: stack27 + loop-edge edit in the two top-k threshold search loops (uniform all-done test as one s_andn2 with exec instead of cndmask/cmp/s_cmp round trip)
# speedup vs baseline: 1.0016x; 1.0012x over previous
.LBB0_1398:
	v_lshlrev_b32_e64 v20, v19, 1
	v_or_b32_e32 v20, v20, v18
	v_mov_b32_e32 v21, 0
	v_cmp_ge_u32_e64 s[0:1], v2, v20
	v_cmp_ge_u32_e64 s[98:99], v3, v20
	v_cmp_ge_u32_e64 s[100:101], v4, v20
	v_cmp_ge_u32_e32 vcc, v5, v20
	v_addc_co_u32_e64 v21, s[0:1], 0, v21, s[0:1]
	v_addc_co_u32_e64 v21, s[98:99], 0, v21, s[98:99]
	v_addc_co_u32_e64 v21, s[100:101], 0, v21, s[100:101]
	v_addc_co_u32_e32 v21, vcc, 0, v21, vcc
	v_cmp_ge_u32_e64 s[0:1], v6, v20
	v_cmp_ge_u32_e64 s[98:99], v7, v20
	v_cmp_ge_u32_e64 s[100:101], v8, v20
	v_cmp_ge_u32_e32 vcc, v9, v20
	v_addc_co_u32_e64 v21, s[0:1], 0, v21, s[0:1]
	v_addc_co_u32_e64 v21, s[98:99], 0, v21, s[98:99]
	v_addc_co_u32_e64 v21, s[100:101], 0, v21, s[100:101]
	v_addc_co_u32_e32 v21, vcc, 0, v21, vcc
	v_cmp_ge_u32_e64 s[0:1], v10, v20
	v_cmp_ge_u32_e64 s[98:99], v11, v20
	v_cmp_ge_u32_e64 s[100:101], v12, v20
	v_cmp_ge_u32_e32 vcc, v13, v20
	v_addc_co_u32_e64 v21, s[0:1], 0, v21, s[0:1]
	v_addc_co_u32_e64 v21, s[98:99], 0, v21, s[98:99]
	v_addc_co_u32_e64 v21, s[100:101], 0, v21, s[100:101]
	v_addc_co_u32_e32 v21, vcc, 0, v21, vcc
	v_cmp_ge_u32_e64 s[0:1], v14, v20
	v_cmp_ge_u32_e64 s[98:99], v15, v20
	v_cmp_ge_u32_e64 s[100:101], v16, v20
	v_cmp_ge_u32_e32 vcc, v17, v20
	v_addc_co_u32_e64 v21, s[0:1], 0, v21, s[0:1]
	v_addc_co_u32_e64 v21, s[98:99], 0, v21, s[98:99]
	v_addc_co_u32_e64 v21, s[100:101], 0, v21, s[100:101]
	v_addc_co_u32_e32 v21, vcc, 0, v21, vcc
	s_nop 1
	v_add_u32_dpp v21, v21, v21 quad_perm:[1,0,3,2] row_mask:0xf bank_mask:0xf bound_ctrl:1
	s_nop 1
	v_add_u32_dpp v21, v21, v21 quad_perm:[2,3,0,1] row_mask:0xf bank_mask:0xf bound_ctrl:1
	s_nop 1
	v_add_u32_dpp v21, v21, v21 row_half_mirror row_mask:0xf bank_mask:0xf bound_ctrl:1
	v_cmp_eq_u32_e64 s[0:1], 13, v21
	v_cmp_gt_i32_e32 vcc, 13, v21
	s_or_b64 s[0:1], s[2:3], s[0:1]
	s_or_b64 vcc, s[2:3], vcc
	s_andn2_b64 s[2:3], exec, s[0:1]
	v_cndmask_b32_e32 v18, v20, v18, vcc
	s_cselect_b64 s[2:3], 0, -1
	v_subrev_co_u32_e32 v19, vcc, 1, v19
	s_or_b64 s[2:3], s[2:3], vcc
	s_andn2_b64 vcc, exec, s[2:3]
	s_mov_b64 s[2:3], s[0:1]
	s_cbranch_vccnz .LBB0_1398

.LBB0_1469:
	s_waitcnt vmcnt(0)
	v_lshlrev_b32_e64 v20, v9, 1
	v_or_b32_e32 v20, v20, v3
	v_mov_b32_e32 v21, 0
	v_cmp_ge_u32_e64 s[0:1], v19, v20
	v_cmp_ge_u32_e64 s[98:99], v17, v20
	v_cmp_ge_u32_e64 s[100:101], v18, v20
	v_cmp_ge_u32_e32 vcc, v15, v20
	v_addc_co_u32_e64 v21, s[0:1], 0, v21, s[0:1]
	v_addc_co_u32_e64 v21, s[98:99], 0, v21, s[98:99]
	v_addc_co_u32_e64 v21, s[100:101], 0, v21, s[100:101]
	v_addc_co_u32_e32 v21, vcc, 0, v21, vcc
	v_cmp_ge_u32_e64 s[0:1], v14, v20
	v_cmp_ge_u32_e64 s[98:99], v13, v20
	v_cmp_ge_u32_e64 s[100:101], v12, v20
	v_cmp_ge_u32_e32 vcc, v11, v20
	v_addc_co_u32_e64 v21, s[0:1], 0, v21, s[0:1]
	v_addc_co_u32_e64 v21, s[98:99], 0, v21, s[98:99]
	v_addc_co_u32_e64 v21, s[100:101], 0, v21, s[100:101]
	v_addc_co_u32_e32 v21, vcc, 0, v21, vcc
	v_cmp_ge_u32_e64 s[0:1], v10, v20
	v_cmp_ge_u32_e64 s[98:99], v8, v20
	v_cmp_ge_u32_e64 s[100:101], v7, v20
	v_cmp_ge_u32_e32 vcc, v6, v20
	v_addc_co_u32_e64 v21, s[0:1], 0, v21, s[0:1]
	v_addc_co_u32_e64 v21, s[98:99], 0, v21, s[98:99]
	v_addc_co_u32_e64 v21, s[100:101], 0, v21, s[100:101]
	v_addc_co_u32_e32 v21, vcc, 0, v21, vcc
	v_cmp_ge_u32_e64 s[0:1], v5, v20
	v_cmp_ge_u32_e64 s[98:99], v4, v20
	v_cmp_ge_u32_e64 s[100:101], v2, v20
	v_cmp_ge_u32_e32 vcc, v16, v20
	v_addc_co_u32_e64 v21, s[0:1], 0, v21, s[0:1]
	v_addc_co_u32_e64 v21, s[98:99], 0, v21, s[98:99]
	v_addc_co_u32_e64 v21, s[100:101], 0, v21, s[100:101]
	v_addc_co_u32_e32 v21, vcc, 0, v21, vcc
	s_nop 1
	v_add_u32_dpp v21, v21, v21 quad_perm:[1,0,3,2] row_mask:0xf bank_mask:0xf bound_ctrl:1
	s_nop 1
	v_add_u32_dpp v21, v21, v21 quad_perm:[2,3,0,1] row_mask:0xf bank_mask:0xf bound_ctrl:1
	s_nop 1
	v_add_u32_dpp v21, v21, v21 row_half_mirror row_mask:0xf bank_mask:0xf bound_ctrl:1
	v_cmp_eq_u32_e64 s[0:1], 13, v21
	v_cmp_gt_i32_e32 vcc, 13, v21
	s_or_b64 s[0:1], s[2:3], s[0:1]
	s_or_b64 vcc, s[2:3], vcc
	s_andn2_b64 s[2:3], exec, s[0:1]
	v_cndmask_b32_e32 v3, v20, v3, vcc
	s_cselect_b64 s[2:3], 0, -1
	v_subrev_co_u32_e32 v9, vcc, 1, v9
	s_or_b64 s[2:3], s[2:3], vcc
	s_andn2_b64 vcc, exec, s[2:3]
	s_mov_b64 s[2:3], s[0:1]
	s_cbranch_vccnz .LBB0_1469
	v_cmp_ne_u32_e32 vcc, 0, v3
	s_and_saveexec_b64 s[0:1], vcc
	s_xor_b64 s[46:47], exec, s[0:1]
	s_cbranch_execz .LBB0_1472
	v_cmp_gt_u32_e64 s[14:15], v19, v3
	v_cmp_gt_u32_e64 s[12:13], v17, v3
	v_cmp_eq_u32_e64 s[2:3], v17, v3
	v_cndmask_b32_e64 v17, 0, 1, s[14:15]
	v_cmp_eq_u32_e64 s[40:41], v19, v3
	v_cmp_gt_u32_e64 s[20:21], v18, v3
	v_addc_co_u32_e64 v17, vcc, 0, v17, s[12:13]
	v_cndmask_b32_e64 v19, 0, 1, s[40:41]
	v_cndmask_b32_e64 v21, 0, 1, s[20:21]
	v_cmp_eq_u32_e64 s[38:39], v18, v3
	v_cmp_gt_u32_e64 s[16:17], v15, v3
	v_cmp_gt_u32_e64 s[10:11], v14, v3
	v_addc_co_u32_e64 v20, vcc, 0, v19, s[2:3]
	v_cndmask_b32_e64 v18, 0, 1, s[38:39]
	v_addc_co_u32_e64 v17, vcc, v17, v21, s[16:17]
	v_cmp_eq_u32_e64 s[8:9], v15, v3
	v_cndmask_b32_e64 v21, 0, 1, s[10:11]
	v_cmp_eq_u32_e64 s[22:23], v14, v3
	v_cmp_gt_u32_e64 s[86:87], v13, v3
	v_cmp_gt_u32_e64 s[36:37], v12, v3
	v_addc_co_u32_e64 v20, vcc, v20, v18, s[8:9]
	v_cndmask_b32_e64 v14, 0, 1, s[22:23]
	v_addc_co_u32_e64 v17, s[0:1], v17, v21, s[86:87]
	v_cmp_eq_u32_e64 s[18:19], v13, v3
	v_cndmask_b32_e64 v21, 0, 1, s[36:37]
	v_cmp_gt_u32_e64 s[4:5], v11, v3
	v_addc_co_u32_e64 v20, s[0:1], v20, v14, s[18:19]
	v_cmp_eq_u32_e64 s[24:25], v12, v3
	v_addc_co_u32_e64 v17, s[0:1], v17, v21, s[4:5]
	v_cmp_gt_u32_e64 s[70:71], v10, v3
	v_cndmask_b32_e64 v12, 0, 1, s[24:25]
	v_cmp_eq_u32_e64 s[0:1], v11, v3
	v_cndmask_b32_e64 v21, 0, 1, s[70:71]
	s_mov_b64 s[28:29], s[84:85]
	s_mov_b64 s[84:85], s[58:59]
	s_mov_b64 s[58:59], s[66:67]
	v_cmp_eq_u32_e64 s[66:67], v10, v3
	v_cmp_gt_u32_e64 s[74:75], v8, v3
	v_cmp_gt_u32_e64 s[72:73], v7, v3
	v_addc_co_u32_e64 v20, s[6:7], v20, v12, s[0:1]
	v_cndmask_b32_e64 v10, 0, 1, s[66:67]
	v_addc_co_u32_e64 v17, s[6:7], v17, v21, s[74:75]
	s_mov_b32 s53, s52
	s_mov_b32 s52, s64
	v_cmp_eq_u32_e64 s[64:65], v8, v3
	v_cndmask_b32_e64 v21, 0, 1, s[72:73]
	v_cmp_gt_u32_e64 s[82:83], v6, v3
	v_addc_co_u32_e64 v20, s[6:7], v20, v10, s[64:65]
	v_cmp_eq_u32_e64 s[68:69], v7, v3
	v_addc_co_u32_e64 v17, s[6:7], v17, v21, s[82:83]
	v_cmp_gt_u32_e64 s[94:95], v5, v3
	v_cndmask_b32_e64 v7, 0, 1, s[68:69]
	v_cmp_eq_u32_e64 s[6:7], v6, v3
	v_cndmask_b32_e64 v21, 0, 1, s[94:95]
	v_cmp_gt_u32_e64 s[90:91], v4, v3
	v_addc_co_u32_e64 v20, s[76:77], v20, v7, s[6:7]
	v_cmp_eq_u32_e64 s[78:79], v5, v3
	v_addc_co_u32_e64 v17, s[76:77], v17, v21, s[90:91]
	s_nop 0
	v_cndmask_b32_e64 v5, 0, 1, s[78:79]
	v_cmp_eq_u32_e64 s[76:77], v4, v3
	v_cmp_gt_u32_e64 s[88:89], v16, v3
	v_cmp_eq_u32_e64 s[96:97], v2, v3
	v_addc_co_u32_e64 v20, s[80:81], v20, v5, s[76:77]
	v_cmp_gt_u32_e64 s[80:81], v2, v3
	s_mov_b32 s34, s92
	v_cndmask_b32_e64 v2, 0, 1, s[96:97]
	v_cndmask_b32_e64 v21, 0, 1, s[80:81]
	v_addc_co_u32_e64 v17, s[92:93], v17, v21, s[88:89]
	v_cmp_eq_u32_e64 s[92:93], v16, v3
	s_nop 0
	v_add_u32_dpp v16, v17, v17 quad_perm:[1,0,3,2] row_mask:0xf bank_mask:0xf bound_ctrl:1
	v_mov_b32_e32 v17, v83
	v_addc_co_u32_e64 v3, vcc, v20, v2, s[92:93]
	v_and_or_b32 v20, v173, 64, v149
	v_lshlrev_b32_e32 v20, 2, v20
	ds_bpermute_b32 v21, v20, v3
	ds_bpermute_b32 v22, v20, v3 offset:4
	v_readlane_b32 vcc_lo, v247, 20
	v_readlane_b32 vcc_hi, v247, 21
	ds_bpermute_b32 v23, v20, v3 offset:8
	v_add_u32_dpp v16, v16, v16 quad_perm:[2,3,0,1] row_mask:0xf bank_mask:0xf bound_ctrl:1
	s_waitcnt lgkmcnt(2)
	v_cndmask_b32_e64 v21, v21, 0, vcc
	v_readlane_b32 vcc_lo, v246, 30
	v_readlane_b32 vcc_hi, v246, 31
	v_mov_b32_dpp v17, v16 row_half_mirror row_mask:0xf bank_mask:0xf
	v_add_u32_e32 v16, v17, v16
	s_waitcnt lgkmcnt(1)
	v_cndmask_b32_e32 v22, 0, v22, vcc
	v_readlane_b32 vcc_lo, v246, 32
	v_readlane_b32 vcc_hi, v246, 33
	v_cndmask_b32_e64 v9, 0, 1, s[2:3]
	v_sub_u32_e32 v16, 13, v16
	s_waitcnt lgkmcnt(0)
	v_cndmask_b32_e32 v23, 0, v23, vcc
	v_add3_u32 v21, v22, v21, v23
	ds_bpermute_b32 v22, v20, v3 offset:12
	ds_bpermute_b32 v23, v20, v3 offset:16
	v_readlane_b32 vcc_lo, v246, 34
	v_readlane_b32 vcc_hi, v246, 35
	v_cndmask_b32_e64 v9, v9, 0, s[12:13]
	v_cndmask_b32_e64 v19, v19, 0, s[14:15]
	s_waitcnt lgkmcnt(1)
	v_cndmask_b32_e32 v22, 0, v22, vcc
	v_readlane_b32 vcc_lo, v246, 36
	v_readlane_b32 vcc_hi, v246, 37
	v_cndmask_b32_e64 v18, v18, 0, s[20:21]
	v_cndmask_b32_e64 v15, 0, 1, s[8:9]
	s_waitcnt lgkmcnt(0)
	v_cndmask_b32_e32 v23, 0, v23, vcc
	v_add3_u32 v21, v21, v22, v23
	ds_bpermute_b32 v22, v20, v3 offset:20
	v_or_b32_e32 v20, 24, v20
	ds_bpermute_b32 v3, v20, v3
	v_readlane_b32 vcc_lo, v246, 38
	v_readlane_b32 vcc_hi, v246, 39
	v_cndmask_b32_e64 v15, v15, 0, s[16:17]
	v_cndmask_b32_e64 v14, v14, 0, s[10:11]
	s_waitcnt lgkmcnt(1)
	v_cndmask_b32_e32 v22, 0, v22, vcc
	v_readlane_b32 vcc_lo, v247, 10
	v_readlane_b32 vcc_hi, v247, 11
	v_cndmask_b32_e64 v13, 0, 1, s[18:19]
	v_cndmask_b32_e64 v13, v13, 0, s[86:87]
	s_waitcnt lgkmcnt(0)
	v_cndmask_b32_e32 v3, 0, v3, vcc
	v_add3_u32 v3, v21, v22, v3
	v_cmp_lt_i32_e32 vcc, v3, v16
	s_and_b64 s[2:3], s[2:3], vcc
	v_add_u32_e32 v3, v3, v9
	s_or_b64 s[2:3], s[12:13], s[2:3]
	v_cmp_lt_i32_e32 vcc, v3, v16
	v_cndmask_b32_e64 v17, 0, 1, s[2:3]
	s_and_b64 s[2:3], s[40:41], vcc
	v_add_u32_e32 v3, v3, v19
	s_or_b64 s[2:3], s[14:15], s[2:3]
	v_cmp_lt_i32_e32 vcc, v3, v16
	v_cndmask_b32_e64 v9, 0, 2, s[2:3]
	s_and_b64 s[2:3], s[38:39], vcc
	v_add_u32_e32 v3, v3, v18
	s_or_b64 s[2:3], s[20:21], s[2:3]
	v_cmp_lt_i32_e32 vcc, v3, v16
	v_or_b32_e32 v9, v9, v17
	v_cndmask_b32_e64 v17, 0, 4, s[2:3]
	s_and_b64 s[2:3], s[8:9], vcc
	v_add_u32_e32 v3, v3, v15
	s_or_b64 s[2:3], s[16:17], s[2:3]
	v_cmp_lt_i32_e32 vcc, v3, v16
	v_cndmask_b32_e64 v18, 0, 8, s[2:3]
	s_and_b64 s[2:3], s[22:23], vcc
	v_add_u32_e32 v3, v3, v14
	s_or_b64 s[2:3], s[10:11], s[2:3]
	v_cmp_lt_i32_e32 vcc, v3, v16
	v_cndmask_b32_e64 v15, 0, 16, s[2:3]
	s_and_b64 s[2:3], s[18:19], vcc
	v_add_u32_e32 v3, v3, v13
	v_cndmask_b32_e64 v12, v12, 0, s[36:37]
	s_or_b64 s[2:3], s[86:87], s[2:3]
	v_cmp_lt_i32_e32 vcc, v3, v16
	v_add_u32_e32 v3, v3, v12
	v_cndmask_b32_e64 v11, 0, 1, s[0:1]
	v_cndmask_b32_e64 v14, 0, 32, s[2:3]
	s_and_b64 s[2:3], s[24:25], vcc
	v_cmp_lt_i32_e32 vcc, v3, v16
	s_and_b64 s[0:1], s[0:1], vcc
	v_cndmask_b32_e64 v11, v11, 0, s[4:5]
	s_or_b64 vcc, s[4:5], s[0:1]
	v_add_u32_e32 v3, v3, v11
	v_cndmask_b32_e32 v12, 0, v174, vcc
	v_cmp_lt_i32_e32 vcc, v3, v16
	s_and_b64 s[0:1], s[66:67], vcc
	v_cndmask_b32_e64 v10, v10, 0, s[70:71]
	s_or_b64 vcc, s[70:71], s[0:1]
	v_add_u32_e32 v3, v3, v10
	v_cndmask_b32_e64 v8, 0, 1, s[64:65]
	v_cndmask_b32_e32 v11, 0, v175, vcc
	v_cmp_lt_i32_e32 vcc, v3, v16
	s_and_b64 s[0:1], s[64:65], vcc
	v_cndmask_b32_e64 v8, v8, 0, s[74:75]
	s_or_b64 vcc, s[74:75], s[0:1]
	v_add_u32_e32 v3, v3, v8
	v_or3_b32 v9, v9, v17, v18
	s_or_b64 s[2:3], s[36:37], s[2:3]
	v_cndmask_b32_e32 v10, 0, v176, vcc
	v_cmp_lt_i32_e32 vcc, v3, v16
	v_or3_b32 v9, v9, v15, v14
	v_cndmask_b32_e64 v13, 0, 64, s[2:3]
	s_and_b64 s[0:1], s[68:69], vcc
	v_cndmask_b32_e64 v7, v7, 0, s[72:73]
	v_or3_b32 v9, v9, v13, v12
	s_or_b64 vcc, s[72:73], s[0:1]
	v_add_u32_e32 v3, v3, v7
	v_cndmask_b32_e64 v6, 0, 1, s[6:7]
	v_or3_b32 v8, v9, v11, v10
	v_cndmask_b32_e32 v9, 0, v177, vcc
	v_cmp_lt_i32_e32 vcc, v3, v16
	s_and_b64 s[0:1], s[6:7], vcc
	v_cndmask_b32_e64 v6, v6, 0, s[82:83]
	s_or_b64 vcc, s[82:83], s[0:1]
	v_add_u32_e32 v3, v3, v6
	v_cndmask_b32_e32 v7, 0, v178, vcc
	v_cmp_lt_i32_e32 vcc, v3, v16
	s_and_b64 s[0:1], s[78:79], vcc
	v_cndmask_b32_e64 v5, v5, 0, s[94:95]
	s_or_b64 vcc, s[94:95], s[0:1]
	v_add_u32_e32 v3, v3, v5
	v_cndmask_b32_e64 v4, 0, 1, s[76:77]
	v_or3_b32 v6, v8, v9, v7
	v_cndmask_b32_e32 v7, 0, v179, vcc
	v_cmp_lt_i32_e32 vcc, v3, v16
	s_and_b64 s[0:1], s[76:77], vcc
	v_cndmask_b32_e64 v4, v4, 0, s[90:91]
	s_or_b64 vcc, s[90:91], s[0:1]
	v_add_u32_e32 v3, v3, v4
	v_cndmask_b32_e32 v5, 0, v180, vcc
	v_cmp_lt_i32_e32 vcc, v3, v16
	s_and_b64 s[0:1], s[96:97], vcc
	v_cndmask_b32_e64 v2, v2, 0, s[80:81]
	s_or_b64 vcc, s[80:81], s[0:1]
	v_add_u32_e32 v2, v3, v2
	v_or3_b32 v4, v6, v7, v5
	v_cndmask_b32_e32 v5, 0, v181, vcc
	v_cmp_lt_i32_e32 vcc, v2, v16
	s_and_b64 s[0:1], s[92:93], vcc
	v_readlane_b32 s94, v247, 42
	v_readlane_b32 s96, v247, 8
	s_or_b64 vcc, s[88:89], s[0:1]
	v_readlane_b32 s86, v248, 40
	v_readlane_b32 s36, v246, 4
	s_mov_b64 s[66:67], s[58:59]
	s_mov_b64 s[58:59], s[84:85]
	s_mov_b64 s[84:85], s[28:29]
	v_readlane_b32 s28, v246, 10
	v_readlane_b32 s70, v246, 2
	v_readlane_b32 s74, v246, 20
	v_readlane_b32 s68, v246, 14
	v_readlane_b32 s72, v246, 18
	v_readlane_b32 s82, v246, 8
	v_readlane_b32 s78, v246, 24
	v_readlane_b32 s95, v247, 43
	v_readlane_b32 s76, v246, 22
	v_readlane_b32 s90, v246, 12
	v_readlane_b32 s97, v247, 9
	v_readlane_b32 s80, v247, 6
	v_cndmask_b32_e32 v2, 0, v87, vcc
	s_movk_i32 s15, 0x280
	s_movk_i32 s14, 0x260
	s_movk_i32 s13, 0x240
	s_movk_i32 s12, 0x220
	s_movk_i32 s23, 0x360
	s_movk_i32 s22, 0x3a0
	s_movk_i32 s21, 0x2c0
	s_mov_b32 s20, 0xff800000
	s_movk_i32 s19, 0x2e0
	s_movk_i32 s18, 0x300
	s_movk_i32 s17, 0x320
	s_movk_i32 s16, 0x340
	v_readlane_b32 s87, v248, 41
	v_readlane_b32 s37, v246, 5
	v_readlane_b32 s29, v246, 11
	v_readlane_b32 s71, v246, 3
	s_movk_i32 s65, 0x200
	s_mov_b32 s64, s52
	s_mov_b32 s52, s53
	s_movk_i32 s53, 0x1e0
	v_readlane_b32 s75, v246, 21
	v_readlane_b32 s69, v246, 15
	v_readlane_b32 s73, v246, 19
	v_readlane_b32 s83, v246, 9
	v_readlane_b32 s79, v246, 25
	s_mov_b32 s95, 0xc000
	v_readlane_b32 s77, v246, 23
	v_readlane_b32 s91, v246, 13
	s_mov_b32 s97, 0xf000
	v_readlane_b32 s81, v247, 7
	s_mov_b32 s93, 0xa000
	s_mov_b32 s92, s34
	s_movk_i32 s34, 0x2a0
	v_or3_b32 v9, v4, v5, v2
